# attention max-reduce via 3 permlane swaps instead of 4 (shared swap for both q sub-tiles)
# speedup vs baseline: 1.0561x; 1.0012x over previous
; __device__ __forceinline__ void attn_items(const Ctx& C, const PV& P, int layer, int ctr_idx, unsigned char* smem) {
;     ...
;             for (int t = 0; t < 4; ++t) {
;                 st[t][0] = (f32x4){0.f, 0.f, 0.f, 0.f}; st[t][1] = (f32x4){0.f, 0.f, 0.f, 0.f};
; #pragma unroll
;                 for (int ks = 0; ks < 2; ++ks) {
;                     const bf16x8 kf = *(const bf16x8*)(sb + (comp * 64 + t * 16 + fr) * 144 + (ks * 32 + fq * 8) * 2);
;                     st[t][0] = __builtin_amdgcn_mfma_f32_16x16x32_bf16(kf, bq[0][ks], st[t][0], 0, 0, 0);
;                     st[t][1] = __builtin_amdgcn_mfma_f32_16x16x32_bf16(kf, bq[1][ks], st[t][1], 0, 0, 0);
;                 }
;             }
;             float mxq[2];
; #pragma unroll
;             for (int qs = 0; qs < 2; ++qs) {
;                 float mx = -1e30f;
; #pragma unroll
;                 for (int t = 0; t < 4; ++t)
; #pragma unroll
;                     for (int r = 0; r < 4; ++r) mx = fmaxf(mx, st[t][qs][r]);
;                 mxq[qs] = mx;
;             }
;             { const float a0 = __shfl_xor(mxq[0], 16), a1 = __shfl_xor(mxq[1], 16); mxq[0] = fmaxf(mxq[0], a0); mxq[1] = fmaxf(mxq[1], a1);
;               const float b0 = __shfl_xor(mxq[0], 32), b1 = __shfl_xor(mxq[1], 32); mxq[0] = fmaxf(mxq[0], b0); mxq[1] = fmaxf(mxq[1], b1); }
; #pragma unroll
;             for (int qs = 0; qs < 2; ++qs) {
;                 const float mx = mxq[qs];
;                 const float mnew = fmaxf(m_run[qs], mx);
;                 const float alpha = __builtin_amdgcn_exp2f(m_run[qs] - mnew);
;                 m_run[qs] = mnew;
;                 float ls = 0.f;
;                 float pv[4][4];
; #pragma unroll
;                 for (int t = 0; t < 4; ++t)
; #pragma unroll
;                     for (int r = 0; r < 4; ++r) { pv[t][r] = __builtin_amdgcn_exp2f(st[t][qs][r] - mnew); ls += pv[t][r]; }
;                 l_run[qs] = l_run[qs] * alpha + ls;
;                 if (__builtin_amdgcn_ballot_w64(alpha != 1.0f) != 0ull) {
; #pragma unroll
;                     for (int a = 0; a < 8; ++a) O[a][qs] = O[a][qs] * alpha;
;                 }
.LBB0_577:
	s_andn2_saveexec_b64 s[60:61], s[60:61]
	s_cbranch_execz .LBB0_583
	s_bitcmp1_b32 s5, 0
	s_cselect_b32 s6, 0x9000, 0
	v_add_u32_e32 v140, s6, v208
	ds_read_b128 v[124:127], v140
	ds_read_b128 v[116:119], v140 offset:64
	ds_read_b128 v[120:123], v140 offset:2304
	ds_read_b128 v[112:115], v140 offset:2368
	ds_read_b128 v[232:235], v140 offset:4608
	ds_read_b128 v[236:239], v140 offset:4672
	ds_read_b128 v[240:243], v140 offset:6912
	ds_read_b128 v[140:143], v140 offset:6976
	s_waitcnt lgkmcnt(7)
	v_mfma_f32_16x16x32_bf16 v[0:3], v[124:127], v[16:19], 0
	v_mfma_f32_16x16x32_bf16 v[8:11], v[124:127], v[24:27], 0
	s_waitcnt lgkmcnt(6)
	v_mfma_f32_16x16x32_bf16 v[0:3], v[116:119], v[20:23], v[0:3]
	v_mfma_f32_16x16x32_bf16 v[8:11], v[116:119], v[28:31], v[8:11]
	s_waitcnt lgkmcnt(5)
	v_mfma_f32_16x16x32_bf16 v[4:7], v[120:123], v[16:19], 0
	v_mfma_f32_16x16x32_bf16 v[12:15], v[120:123], v[24:27], 0
	s_waitcnt lgkmcnt(4)
	v_mfma_f32_16x16x32_bf16 v[4:7], v[112:115], v[20:23], v[4:7]
	v_mfma_f32_16x16x32_bf16 v[12:15], v[112:115], v[28:31], v[12:15]
	s_waitcnt lgkmcnt(3)
	v_mfma_f32_16x16x32_bf16 v[120:123], v[232:235], v[16:19], 0
	v_mfma_f32_16x16x32_bf16 v[112:115], v[232:235], v[24:27], 0
	s_waitcnt lgkmcnt(2)
	v_mfma_f32_16x16x32_bf16 v[120:123], v[236:239], v[20:23], v[120:123]
	v_mfma_f32_16x16x32_bf16 v[112:115], v[236:239], v[28:31], v[112:115]
	s_waitcnt lgkmcnt(1)
	v_mfma_f32_16x16x32_bf16 v[124:127], v[240:243], v[16:19], 0
	v_mfma_f32_16x16x32_bf16 v[116:119], v[240:243], v[24:27], 0
	s_waitcnt lgkmcnt(0)
	v_mfma_f32_16x16x32_bf16 v[124:127], v[140:143], v[20:23], v[124:127]
	v_mfma_f32_16x16x32_bf16 v[116:119], v[140:143], v[28:31], v[116:119]
	v_max3_f32 v140, v0, s81, v1
	v_max3_f32 v141, v8, s81, v9
	v_max3_f32 v140, v140, v2, v3
	v_max3_f32 v141, v141, v10, v11
	v_max3_f32 v140, v140, v4, v5
	v_max3_f32 v141, v141, v12, v13
	v_max3_f32 v140, v140, v6, v7
	v_max3_f32 v141, v141, v14, v15
	v_max3_f32 v140, v140, v120, v121
	v_max3_f32 v141, v141, v112, v113
	v_max3_f32 v140, v140, v122, v123
	v_max3_f32 v141, v141, v114, v115
	v_max3_f32 v140, v140, v124, v125
	v_max3_f32 v141, v141, v116, v117
	v_max3_f32 v140, v140, v126, v127
	v_max3_f32 v141, v141, v118, v119
	s_nop 1
	v_permlane16_swap_b32_e32 v140, v141
	v_max_f32_e32 v232, v140, v141
	v_mov_b32_e32 v233, v232
	s_nop 1
	v_permlane32_swap_b32_e32 v232, v233
	v_max_f32_e32 v232, v232, v233
	v_mov_b32_e32 v234, v232
	s_nop 1
	v_permlane16_swap_b32_e32 v232, v234
	v_max_f32_e32 v236, v248, v232
	v_max_f32_e32 v237, v249, v234
	v_sub_f32_e32 v238, v248, v236
	v_sub_f32_e32 v239, v249, v237
	v_exp_f32_e32 v244, v238
	v_exp_f32_e32 v246, v239
	v_mov_b32_e32 v248, v236
	v_mov_b32_e32 v249, v237
	v_cmp_neq_f32_e32 vcc, 1.0, v244
	s_cbranch_vccz .Lh1_g0_a
	v_pk_mul_f32 v[110:111], v[110:111], v[244:245] op_sel_hi:[1,0]
	v_pk_mul_f32 v[108:109], v[108:109], v[244:245] op_sel_hi:[1,0]
	v_pk_mul_f32 v[106:107], v[106:107], v[244:245] op_sel_hi:[1,0]
	v_pk_mul_f32 v[104:105], v[104:105], v[244:245] op_sel_hi:[1,0]
	v_pk_mul_f32 v[102:103], v[102:103], v[244:245] op_sel_hi:[1,0]
	v_pk_mul_f32 v[100:101], v[100:101], v[244:245] op_sel_hi:[1,0]
	v_pk_mul_f32 v[98:99], v[98:99], v[244:245] op_sel_hi:[1,0]
	v_pk_mul_f32 v[96:97], v[96:97], v[244:245] op_sel_hi:[1,0]
	v_pk_mul_f32 v[94:95], v[94:95], v[244:245] op_sel_hi:[1,0]
	v_pk_mul_f32 v[92:93], v[92:93], v[244:245] op_sel_hi:[1,0]
	v_pk_mul_f32 v[86:87], v[86:87], v[244:245] op_sel_hi:[1,0]
	v_pk_mul_f32 v[84:85], v[84:85], v[244:245] op_sel_hi:[1,0]
	v_pk_mul_f32 v[78:79], v[78:79], v[244:245] op_sel_hi:[1,0]
	v_pk_mul_f32 v[76:77], v[76:77], v[244:245] op_sel_hi:[1,0]
	v_pk_mul_f32 v[66:67], v[66:67], v[244:245] op_sel_hi:[1,0]
	v_pk_mul_f32 v[64:65], v[64:65], v[244:245] op_sel_hi:[1,0]

; __device__ __forceinline__ void attn_items(const Ctx& C, const PV& P, int layer, int ctr_idx, unsigned char* smem) {
;     ...
;             for (int t = 0; t < 4; ++t) {
;                 st[t][0] = (f32x4){0.f, 0.f, 0.f, 0.f}; st[t][1] = (f32x4){0.f, 0.f, 0.f, 0.f};
; #pragma unroll
;                 for (int ks = 0; ks < 2; ++ks) {
;                     const bf16x8 kf = *(const bf16x8*)(sb + (comp * 64 + t * 16 + fr) * 144 + (ks * 32 + fq * 8) * 2);
;                     st[t][0] = __builtin_amdgcn_mfma_f32_16x16x32_bf16(kf, bq[0][ks], st[t][0], 0, 0, 0);
;                     st[t][1] = __builtin_amdgcn_mfma_f32_16x16x32_bf16(kf, bq[1][ks], st[t][1], 0, 0, 0);
;                 }
;             }
;             float mxq[2];
; #pragma unroll
;             for (int qs = 0; qs < 2; ++qs) {
;                 float mx = -1e30f;
; #pragma unroll
;                 for (int t = 0; t < 4; ++t)
; #pragma unroll
;                     for (int r = 0; r < 4; ++r) mx = fmaxf(mx, st[t][qs][r]);
;                 mxq[qs] = mx;
;             }
;             { const float a0 = __shfl_xor(mxq[0], 16), a1 = __shfl_xor(mxq[1], 16); mxq[0] = fmaxf(mxq[0], a0); mxq[1] = fmaxf(mxq[1], a1);
;               const float b0 = __shfl_xor(mxq[0], 32), b1 = __shfl_xor(mxq[1], 32); mxq[0] = fmaxf(mxq[0], b0); mxq[1] = fmaxf(mxq[1], b1); }
; #pragma unroll
;             for (int qs = 0; qs < 2; ++qs) {
;                 const float mx = mxq[qs];
;                 const float mnew = fmaxf(m_run[qs], mx);
;                 const float alpha = __builtin_amdgcn_exp2f(m_run[qs] - mnew);
;                 m_run[qs] = mnew;
;                 float ls = 0.f;
;                 float pv[4][4];
; #pragma unroll
;                 for (int t = 0; t < 4; ++t)
; #pragma unroll
;                     for (int r = 0; r < 4; ++r) { pv[t][r] = __builtin_amdgcn_exp2f(st[t][qs][r] - mnew); ls += pv[t][r]; }
;                 l_run[qs] = l_run[qs] * alpha + ls;
;                 if (__builtin_amdgcn_ballot_w64(alpha != 1.0f) != 0ull) {
; #pragma unroll
;                     for (int a = 0; a < 8; ++a) O[a][qs] = O[a][qs] * alpha;
;                 }
.LBB0_585:
	s_or_b64 exec, exec, s[60:61]
	s_bitcmp1_b32 s5, 0
	s_cselect_b32 s5, 0x9000, 0
	s_and_saveexec_b64 s[6:7], s[42:43]
	s_xor_b64 s[50:51], exec, s[6:7]
	s_cbranch_execz .LBB0_591
	v_add_u32_e32 v140, s5, v208
	ds_read_b128 v[124:127], v140
	ds_read_b128 v[116:119], v140 offset:64
	ds_read_b128 v[120:123], v140 offset:2304
	ds_read_b128 v[112:115], v140 offset:2368
	ds_read_b128 v[232:235], v140 offset:4608
	ds_read_b128 v[236:239], v140 offset:4672
	ds_read_b128 v[240:243], v140 offset:6912
	ds_read_b128 v[140:143], v140 offset:6976
	s_waitcnt lgkmcnt(7)
	v_mfma_f32_16x16x32_bf16 v[0:3], v[124:127], v[16:19], 0
	v_mfma_f32_16x16x32_bf16 v[8:11], v[124:127], v[24:27], 0
	s_waitcnt lgkmcnt(6)
	v_mfma_f32_16x16x32_bf16 v[0:3], v[116:119], v[20:23], v[0:3]
	v_mfma_f32_16x16x32_bf16 v[8:11], v[116:119], v[28:31], v[8:11]
	s_waitcnt lgkmcnt(5)
	v_mfma_f32_16x16x32_bf16 v[4:7], v[120:123], v[16:19], 0
	v_mfma_f32_16x16x32_bf16 v[12:15], v[120:123], v[24:27], 0
	s_waitcnt lgkmcnt(4)
	v_mfma_f32_16x16x32_bf16 v[4:7], v[112:115], v[20:23], v[4:7]
	v_mfma_f32_16x16x32_bf16 v[12:15], v[112:115], v[28:31], v[12:15]
	s_waitcnt lgkmcnt(3)
	v_mfma_f32_16x16x32_bf16 v[120:123], v[232:235], v[16:19], 0
	v_mfma_f32_16x16x32_bf16 v[112:115], v[232:235], v[24:27], 0
	s_waitcnt lgkmcnt(2)
	v_mfma_f32_16x16x32_bf16 v[120:123], v[236:239], v[20:23], v[120:123]
	v_mfma_f32_16x16x32_bf16 v[112:115], v[236:239], v[28:31], v[112:115]
	s_waitcnt lgkmcnt(1)
	v_mfma_f32_16x16x32_bf16 v[124:127], v[240:243], v[16:19], 0
	v_mfma_f32_16x16x32_bf16 v[116:119], v[240:243], v[24:27], 0
	s_waitcnt lgkmcnt(0)
	v_mfma_f32_16x16x32_bf16 v[124:127], v[140:143], v[20:23], v[124:127]
	v_mfma_f32_16x16x32_bf16 v[116:119], v[140:143], v[28:31], v[116:119]
	v_max3_f32 v140, v0, s81, v1
	v_max3_f32 v141, v8, s81, v9
	v_max3_f32 v140, v140, v2, v3
	v_max3_f32 v141, v141, v10, v11
	v_max3_f32 v140, v140, v4, v5
	v_max3_f32 v141, v141, v12, v13
	v_max3_f32 v140, v140, v6, v7
	v_max3_f32 v141, v141, v14, v15
	v_max3_f32 v140, v140, v120, v121
	v_max3_f32 v141, v141, v112, v113
	v_max3_f32 v140, v140, v122, v123
	v_max3_f32 v141, v141, v114, v115
	v_max3_f32 v140, v140, v124, v125
	v_max3_f32 v141, v141, v116, v117
	v_max3_f32 v140, v140, v126, v127
	v_max3_f32 v141, v141, v118, v119
	s_nop 1
	v_permlane16_swap_b32_e32 v140, v141
	v_max_f32_e32 v232, v140, v141
	v_mov_b32_e32 v233, v232
	s_nop 1
	v_permlane32_swap_b32_e32 v232, v233
	v_max_f32_e32 v232, v232, v233
	v_mov_b32_e32 v234, v232
	s_nop 1
	v_permlane16_swap_b32_e32 v232, v234
	v_max_f32_e32 v236, v248, v232
	v_max_f32_e32 v237, v249, v234
	v_sub_f32_e32 v238, v248, v236
	v_sub_f32_e32 v239, v249, v237
	v_exp_f32_e32 v244, v238
	v_exp_f32_e32 v246, v239
	v_mov_b32_e32 v248, v236
	v_mov_b32_e32 v249, v237
	v_cmp_neq_f32_e32 vcc, 1.0, v244
	s_cbranch_vccz .Lh1_g1_a
	v_pk_mul_f32 v[110:111], v[110:111], v[244:245] op_sel_hi:[1,0]
	v_pk_mul_f32 v[108:109], v[108:109], v[244:245] op_sel_hi:[1,0]
	v_pk_mul_f32 v[106:107], v[106:107], v[244:245] op_sel_hi:[1,0]
	v_pk_mul_f32 v[104:105], v[104:105], v[244:245] op_sel_hi:[1,0]
	v_pk_mul_f32 v[102:103], v[102:103], v[244:245] op_sel_hi:[1,0]
	v_pk_mul_f32 v[100:101], v[100:101], v[244:245] op_sel_hi:[1,0]
	v_pk_mul_f32 v[98:99], v[98:99], v[244:245] op_sel_hi:[1,0]
	v_pk_mul_f32 v[96:97], v[96:97], v[244:245] op_sel_hi:[1,0]
	v_pk_mul_f32 v[94:95], v[94:95], v[244:245] op_sel_hi:[1,0]
	v_pk_mul_f32 v[92:93], v[92:93], v[244:245] op_sel_hi:[1,0]
	v_pk_mul_f32 v[86:87], v[86:87], v[244:245] op_sel_hi:[1,0]
	v_pk_mul_f32 v[84:85], v[84:85], v[244:245] op_sel_hi:[1,0]
	v_pk_mul_f32 v[78:79], v[78:79], v[244:245] op_sel_hi:[1,0]
	v_pk_mul_f32 v[76:77], v[76:77], v[244:245] op_sel_hi:[1,0]
	v_pk_mul_f32 v[66:67], v[66:67], v[244:245] op_sel_hi:[1,0]
	v_pk_mul_f32 v[64:65], v[64:65], v[244:245] op_sel_hi:[1,0]
